# v18 + window loop keeps O accumulator in place (drops 32 v_mov_b64 per tile)
# speedup vs baseline: 1.0029x; 1.0029x over previous
.LBB0_864:
	s_add_i32 s40, s73, 2
	s_cmp_gt_i32 s40, s66
	s_cselect_b64 s[18:19], -1, 0
	s_add_i32 s74, s40, s65
	s_cmp_eq_u32 s72, s73
	s_cselect_b32 s75, s67, s21
	s_and_b64 s[40:41], s[18:19], exec
	s_cselect_b32 s40, s68, s22
	s_cselect_b32 s74, s75, s74
	v_mov_b32_e32 v0, v165
	s_cselect_b32 s41, s69, s23
	s_add_u32 s40, s40, s3
	s_addc_u32 s41, s41, 0
	v_ashrrev_i32_e32 v34, 3, v0
	s_lshl_b32 s74, s74, 6
	v_add_u32_e32 v34, s74, v34
	s_and_b64 s[18:19], s[18:19], exec
	v_ashrrev_i32_e32 v35, 31, v34
	s_cselect_b32 s18, 10, 9
	v_lshlrev_b64 v[34:35], s18, v[34:35]
	v_lshlrev_b32_e32 v0, 4, v0
	v_lshl_add_u64 v[34:35], v[34:35], 1, s[40:41]
	v_and_b32_e32 v0, 0x70, v0
	v_lshl_add_u64 v[34:35], v[34:35], 0, v[0:1]
	v_mov_b32_e32 v0, v165
	global_load_dwordx4 v[90:93], v[34:35], off
	s_cmp_le_i32 s70, s25
	v_ashrrev_i32_e32 v34, 3, v0
	v_add_u32_e32 v34, s74, v34
	v_ashrrev_i32_e32 v35, 31, v34
	v_lshlrev_b64 v[34:35], s18, v[34:35]
	v_lshlrev_b32_e32 v0, 4, v0
	v_lshl_add_u64 v[34:35], v[34:35], 1, s[40:41]
	v_and_b32_e32 v0, 0x70, v0
	v_lshl_add_u64 v[34:35], v[34:35], 0, v[0:1]
	global_load_dwordx4 v[94:97], v[34:35], off offset:512
	s_cselect_b64 s[18:19], -1, 0
	s_add_i32 s40, s33, s70
	s_addk_i32 s40, 0xedc1
	s_cmpk_gt_i32 s40, 0xfdff
	s_cselect_b64 s[40:41], -1, 0
	s_and_b64 s[18:19], s[18:19], s[40:41]
	s_mul_i32 s40, s64, 0x2400
	v_add_u32_e32 v126, s40, v184
	ds_read_b128 v[110:113], v126
	ds_read_b128 v[106:109], v126 offset:32
	ds_read_b128 v[98:101], v126 offset:64
	ds_read_b128 v[102:105], v126 offset:96
	s_mul_i32 s74, s64, 0x3000
	s_andn2_b64 vcc, exec, s[18:19]
	s_mov_b64 s[18:19], -1
	s_cbranch_vccz .LBB0_868
	s_waitcnt lgkmcnt(3)
	v_mfma_f32_32x32x16_bf16 v[44:59], v[110:113], v[66:69], 0
	v_mov_b32_e32 v0, v123
	ds_read_b128 v[34:37], v126 offset:4608
	ds_read_b128 v[60:63], v126 offset:4640
	ds_read_b128 v[128:131], v126 offset:4672
	ds_read_b128 v[190:193], v126 offset:4704
	s_nop 0
	v_add_u32_e32 v127, -1, v0
	v_cvt_f32_u32_e32 v38, v0
	s_waitcnt lgkmcnt(6)
	v_mfma_f32_32x32x16_bf16 v[44:59], v[106:109], v[70:73], v[44:59]
	v_cvt_f32_u32_e32 v39, v127
	v_add_u32_e32 v132, -3, v0
	v_add_u32_e32 v133, -2, v0
	v_cvt_f32_u32_e32 v41, v132
	v_cvt_f32_u32_e32 v40, v133
	v_add_u32_e32 v135, -5, v0
	v_add_u32_e32 v139, -4, v0
	s_waitcnt lgkmcnt(5)
	v_mfma_f32_32x32x16_bf16 v[44:59], v[98:101], v[74:77], v[44:59]
	v_cvt_f32_u32_e32 v43, v135
	v_cvt_f32_u32_e32 v42, v139
	v_cmp_gt_u32_e32 vcc, s81, v127
	v_add_u32_e32 v127, -7, v0
	v_add_u32_e32 v188, -6, v0
	s_waitcnt lgkmcnt(4)
	v_mfma_f32_32x32x16_bf16 v[44:59], v[102:105], v[78:81], v[44:59]
	s_nop 11
	v_pk_fma_f32 v[38:39], v[118:119], v[38:39], v[44:45] neg_lo:[1,0,0] neg_hi:[1,0,0]
	v_pk_fma_f32 v[40:41], v[118:119], v[40:41], v[46:47] neg_lo:[1,0,0] neg_hi:[1,0,0]
	v_cndmask_b32_e32 v137, v144, v39, vcc
	v_cmp_gt_u32_e32 vcc, s81, v0
	v_pk_fma_f32 v[64:65], v[118:119], v[42:43], v[48:49] neg_lo:[1,0,0] neg_hi:[1,0,0]
	s_nop 0
	v_cndmask_b32_e32 v138, v144, v38, vcc
	v_cmp_gt_u32_e32 vcc, s81, v132
	v_max3_f32 v38, v138, s28, v137
	v_cvt_f32_u32_e32 v132, v188
	v_cndmask_b32_e32 v134, v144, v41, vcc
	v_cmp_gt_u32_e32 vcc, s81, v133
	v_cvt_f32_u32_e32 v133, v127
	v_pk_fma_f32 v[50:51], v[118:119], v[132:133], v[50:51] neg_lo:[1,0,0] neg_hi:[1,0,0]
	v_cndmask_b32_e32 v136, v144, v40, vcc
	v_cmp_gt_u32_e32 vcc, s81, v135
	s_nop 1
	v_cndmask_b32_e32 v135, v144, v65, vcc
	v_max3_f32 v65, v38, v136, v134
	s_waitcnt lgkmcnt(3)
	v_mfma_f32_32x32x16_bf16 v[34:49], v[34:37], v[66:69], 0
	v_cmp_gt_u32_e32 vcc, s81, v139
	s_nop 1
	v_cndmask_b32_e32 v187, v144, v64, vcc
	v_cmp_gt_u32_e32 vcc, s81, v127
	v_max3_f32 v64, v65, v187, v135
	v_mov_b32_e32 v127, v124
	s_waitcnt lgkmcnt(2)
	v_mfma_f32_32x32x16_bf16 v[34:49], v[60:63], v[70:73], v[34:49]
	v_add_u32_e32 v62, -16, v0
	v_subrev_u32_e32 v63, 17, v0
	v_cvt_f32_u32_e32 v60, v62
	v_cvt_f32_u32_e32 v61, v63
	v_cndmask_b32_e32 v186, v144, v51, vcc
	v_cmp_gt_u32_e32 vcc, s81, v188
	s_waitcnt lgkmcnt(1)
	v_mfma_f32_32x32x16_bf16 v[34:49], v[128:131], v[74:77], v[34:49]
	v_cndmask_b32_e32 v189, v144, v50, vcc
	v_fma_f32 v50, -v118, v60, v52
	v_fma_f32 v51, -v119, v61, v53
	v_subrev_u32_e32 v60, 19, v0
	v_subrev_u32_e32 v61, 18, v0
	v_cvt_f32_u32_e32 v53, v60
	v_cvt_f32_u32_e32 v52, v61
	v_cmp_gt_u32_e32 vcc, s81, v63
	s_waitcnt lgkmcnt(0)
	v_mfma_f32_32x32x16_bf16 v[34:49], v[190:193], v[78:81], v[34:49]
	v_max3_f32 v64, v64, v189, v186
	v_cndmask_b32_e32 v188, v144, v51, vcc
	v_cmp_gt_u32_e32 vcc, s81, v62
	s_nop 1
	v_cndmask_b32_e32 v191, v144, v50, vcc
	v_fma_f32 v50, -v118, v52, v54
	v_fma_f32 v51, -v119, v53, v55
	v_subrev_u32_e32 v54, 21, v0
	v_subrev_u32_e32 v55, 20, v0
	v_cvt_f32_u32_e32 v53, v54
	v_cvt_f32_u32_e32 v52, v55
	v_cmp_gt_u32_e32 vcc, s81, v60
	v_max3_f32 v62, v64, v191, v188
	s_nop 0
	v_cndmask_b32_e32 v190, v144, v51, vcc
	v_cmp_gt_u32_e32 vcc, s81, v61
	s_nop 1
	v_cndmask_b32_e32 v193, v144, v50, vcc
	v_pk_fma_f32 v[50:51], v[118:119], v[52:53], v[56:57] neg_lo:[1,0,0] neg_hi:[1,0,0]
	v_cmp_gt_u32_e32 vcc, s81, v54
	v_subrev_u32_e32 v54, 23, v0
	v_subrev_u32_e32 v56, 22, v0
	v_cvt_f32_u32_e32 v53, v54
	v_cvt_f32_u32_e32 v52, v56
	v_cndmask_b32_e32 v192, v144, v51, vcc
	v_cmp_gt_u32_e32 vcc, s81, v55
	v_max3_f32 v60, v62, v193, v190
	s_nop 0
	v_cndmask_b32_e32 v196, v144, v50, vcc
	v_pk_fma_f32 v[50:51], v[118:119], v[52:53], v[58:59] neg_lo:[1,0,0] neg_hi:[1,0,0]
	v_cmp_gt_u32_e32 vcc, s81, v54
	v_subrev_u32_e32 v54, 32, v0
	v_cvt_f32_u32_e32 v52, v54
	v_cndmask_b32_e32 v194, v144, v51, vcc
	v_subrev_u32_e32 v51, 33, v0
	v_cvt_f32_u32_e32 v53, v51
	v_cmp_gt_u32_e32 vcc, s81, v56
	v_max3_f32 v55, v60, v196, v192
	v_pk_fma_f32 v[34:35], v[118:119], v[52:53], v[34:35] neg_lo:[1,0,0] neg_hi:[1,0,0]
	v_subrev_u32_e32 v52, 35, v0
	v_subrev_u32_e32 v53, 34, v0
	v_cndmask_b32_e32 v198, v144, v50, vcc
	v_cmp_gt_u32_e32 vcc, s81, v51
	v_cvt_f32_u32_e32 v51, v52
	v_cvt_f32_u32_e32 v50, v53
	v_cndmask_b32_e32 v195, v144, v35, vcc
	v_cmp_gt_u32_e32 vcc, s81, v54
	v_max3_f32 v55, v55, v198, v194
	s_nop 0
	v_cndmask_b32_e32 v199, v144, v34, vcc
	v_pk_fma_f32 v[34:35], v[118:119], v[50:51], v[36:37] neg_lo:[1,0,0] neg_hi:[1,0,0]
	v_subrev_u32_e32 v50, 37, v0
	v_subrev_u32_e32 v51, 36, v0
	v_cvt_f32_u32_e32 v37, v50
	v_cvt_f32_u32_e32 v36, v51
	v_cmp_gt_u32_e32 vcc, s81, v52
	v_max3_f32 v54, v55, v199, v195
	s_nop 0
	v_cndmask_b32_e32 v197, v144, v35, vcc
	v_cmp_gt_u32_e32 vcc, s81, v53
	s_nop 1
	v_cndmask_b32_e32 v201, v144, v34, vcc
	v_pk_fma_f32 v[34:35], v[118:119], v[36:37], v[38:39] neg_lo:[1,0,0] neg_hi:[1,0,0]
	v_subrev_u32_e32 v38, 39, v0
	v_subrev_u32_e32 v39, 38, v0
	v_cvt_f32_u32_e32 v37, v38
	v_cvt_f32_u32_e32 v36, v39
	v_cmp_gt_u32_e32 vcc, s81, v50
	v_max3_f32 v52, v54, v201, v197
	s_nop 0
	v_cndmask_b32_e32 v200, v144, v35, vcc
	v_cmp_gt_u32_e32 vcc, s81, v51
	s_nop 1
	v_cndmask_b32_e32 v203, v144, v34, vcc
	v_pk_fma_f32 v[34:35], v[118:119], v[36:37], v[40:41] neg_lo:[1,0,0] neg_hi:[1,0,0]
	v_cmp_gt_u32_e32 vcc, s81, v38
	v_subrev_u32_e32 v38, 49, v0
	v_subrev_u32_e32 v40, 48, v0
	v_cvt_f32_u32_e32 v37, v38
	v_cvt_f32_u32_e32 v36, v40
	v_cndmask_b32_e32 v202, v144, v35, vcc
	v_cmp_gt_u32_e32 vcc, s81, v39
	v_subrev_u32_e32 v41, 50, v0
	v_max3_f32 v50, v52, v203, v200
	v_cndmask_b32_e32 v205, v144, v34, vcc
	v_cmp_gt_u32_e32 vcc, s81, v38
	v_subrev_u32_e32 v38, 51, v0
	v_pk_fma_f32 v[34:35], v[118:119], v[36:37], v[42:43] neg_lo:[1,0,0] neg_hi:[1,0,0]
	v_cvt_f32_u32_e32 v37, v38
	v_cvt_f32_u32_e32 v36, v41
	v_cndmask_b32_e32 v204, v144, v35, vcc
	v_cmp_gt_u32_e32 vcc, s81, v40
	v_subrev_u32_e32 v40, 52, v0
	v_max3_f32 v39, v50, v205, v202
	v_cndmask_b32_e32 v139, v144, v34, vcc
	v_cmp_gt_u32_e32 vcc, s81, v38
	v_subrev_u32_e32 v38, 53, v0
	v_pk_fma_f32 v[34:35], v[118:119], v[36:37], v[44:45] neg_lo:[1,0,0] neg_hi:[1,0,0]
	v_cvt_f32_u32_e32 v37, v38
	v_cvt_f32_u32_e32 v36, v40
	v_cndmask_b32_e32 v132, v144, v35, vcc
	v_cmp_gt_u32_e32 vcc, s81, v41
	v_max3_f32 v39, v39, v139, v204
	s_nop 0
	v_cndmask_b32_e32 v133, v144, v34, vcc
	v_cmp_gt_u32_e32 vcc, s81, v38
	v_subrev_u32_e32 v38, 55, v0
	v_subrev_u32_e32 v0, 54, v0
	v_pk_fma_f32 v[34:35], v[118:119], v[36:37], v[46:47] neg_lo:[1,0,0] neg_hi:[1,0,0]
	v_cvt_f32_u32_e32 v37, v38
	v_cvt_f32_u32_e32 v36, v0
	v_cndmask_b32_e32 v131, v144, v35, vcc
	v_cmp_gt_u32_e32 vcc, s81, v40
	v_max3_f32 v39, v39, v133, v132
	s_nop 0
	v_cndmask_b32_e32 v129, v144, v34, vcc
	v_pk_fma_f32 v[34:35], v[118:119], v[36:37], v[48:49] neg_lo:[1,0,0] neg_hi:[1,0,0]
	v_cmp_gt_u32_e32 vcc, s81, v38
	v_max3_f32 v39, v39, v129, v131
	s_nop 0
	v_cndmask_b32_e32 v130, v144, v35, vcc
	v_cmp_gt_u32_e32 vcc, s81, v0
	v_and_b32_e32 v35, 64, v228
	v_add_u32_e32 v35, 64, v35
	v_cndmask_b32_e32 v128, v144, v34, vcc
	v_xor_b32_e32 v34, 32, v228
	v_cmp_lt_i32_e32 vcc, v34, v35
	v_max3_f32 v0, v39, v128, v130
	s_nop 0
	v_cndmask_b32_e32 v34, v228, v34, vcc
	v_lshlrev_b32_e32 v34, 2, v34
	ds_bpermute_b32 v34, v34, v0
	s_waitcnt lgkmcnt(0)
	v_max3_f32 v0, v125, v0, v34
	v_cmp_gt_f32_e32 vcc, v0, v125
	s_cbranch_vccz .LBB0_867
	v_sub_f32_e32 v34, v125, v0
	v_exp_f32_e32 v34, v34
	s_nop 0
	v_mul_f32_e32 v127, v124, v34
	v_pk_mul_f32 v[32:33], v[32:33], v[34:35] op_sel_hi:[1,0]
	v_pk_mul_f32 v[30:31], v[30:31], v[34:35] op_sel_hi:[1,0]
	v_pk_mul_f32 v[28:29], v[28:29], v[34:35] op_sel_hi:[1,0]
	v_pk_mul_f32 v[26:27], v[26:27], v[34:35] op_sel_hi:[1,0]
	v_pk_mul_f32 v[24:25], v[24:25], v[34:35] op_sel_hi:[1,0]
	v_pk_mul_f32 v[22:23], v[22:23], v[34:35] op_sel_hi:[1,0]
	v_pk_mul_f32 v[20:21], v[20:21], v[34:35] op_sel_hi:[1,0]
	v_pk_mul_f32 v[18:19], v[18:19], v[34:35] op_sel_hi:[1,0]
	v_pk_mul_f32 v[16:17], v[16:17], v[34:35] op_sel_hi:[1,0]
	v_pk_mul_f32 v[14:15], v[14:15], v[34:35] op_sel_hi:[1,0]
	v_pk_mul_f32 v[12:13], v[12:13], v[34:35] op_sel_hi:[1,0]
	v_pk_mul_f32 v[10:11], v[10:11], v[34:35] op_sel_hi:[1,0]
	v_pk_mul_f32 v[8:9], v[8:9], v[34:35] op_sel_hi:[1,0]
	v_pk_mul_f32 v[6:7], v[6:7], v[34:35] op_sel_hi:[1,0]
	v_pk_mul_f32 v[4:5], v[4:5], v[34:35] op_sel_hi:[1,0]
	v_pk_mul_f32 v[2:3], v[2:3], v[34:35] op_sel_hi:[1,0]
.LBB0_867:
	v_sub_f32_e32 v206, v137, v0
	v_exp_f32_e32 v206, v206
	v_sub_f32_e32 v207, v138, v0
	v_exp_f32_e32 v207, v207
	v_cmp_lt_f32_e32 vcc, s29, v137
	v_sub_f32_e32 v208, v136, v0
	v_exp_f32_e32 v208, v208
	v_cndmask_b32_e32 v206, 0, v206, vcc
	v_cmp_lt_f32_e32 vcc, s29, v138
	v_add_u32_e32 v218, s74, v182
	s_mov_b64 s[18:19], 0
	v_cndmask_b32_e32 v138, 0, v207, vcc
	v_sub_f32_e32 v207, v134, v0
	v_exp_f32_e32 v207, v207
	v_cmp_lt_f32_e32 vcc, s29, v134
	v_add_f32_e32 v137, 0, v138
	v_add_f32_e32 v137, v206, v137
	v_cndmask_b32_e32 v207, 0, v207, vcc
	v_cmp_lt_f32_e32 vcc, s29, v136
	v_sub_f32_e32 v136, v135, v0
	v_exp_f32_e32 v136, v136
	v_cndmask_b32_e32 v208, 0, v208, vcc
	v_add_f32_e32 v134, v208, v137
	v_sub_f32_e32 v137, v187, v0
	v_exp_f32_e32 v137, v137
	v_cmp_lt_f32_e32 vcc, s29, v135
	v_sub_f32_e32 v135, v186, v0
	v_exp_f32_e32 v135, v135
	v_cndmask_b32_e32 v209, 0, v136, vcc
	v_sub_f32_e32 v136, v189, v0
	v_exp_f32_e32 v136, v136
	v_cmp_lt_f32_e32 vcc, s29, v187
	v_add_f32_e32 v134, v207, v134
	v_cvt_pk_bf16_f32 v187, v208, v207
	v_cndmask_b32_e32 v210, 0, v137, vcc
	v_cmp_lt_f32_e32 vcc, s29, v186
	v_add_f32_e32 v134, v210, v134
	v_add_f32_e32 v134, v209, v134
	v_cndmask_b32_e32 v211, 0, v135, vcc
	v_cmp_lt_f32_e32 vcc, s29, v189
	v_sub_f32_e32 v135, v188, v0
	v_exp_f32_e32 v135, v135
	v_cndmask_b32_e32 v189, 0, v136, vcc
	v_sub_f32_e32 v136, v191, v0
	v_exp_f32_e32 v136, v136
	v_cmp_lt_f32_e32 vcc, s29, v188
	v_add_f32_e32 v134, v189, v134
	v_add_f32_e32 v134, v211, v134
	v_cndmask_b32_e32 v212, 0, v135, vcc
	v_cmp_lt_f32_e32 vcc, s29, v191
	v_sub_f32_e32 v135, v190, v0
	v_exp_f32_e32 v135, v135
	v_cndmask_b32_e32 v213, 0, v136, vcc
	v_sub_f32_e32 v136, v193, v0
	v_exp_f32_e32 v136, v136
	v_cmp_lt_f32_e32 vcc, s29, v190
	v_add_f32_e32 v134, v213, v134
	v_add_f32_e32 v134, v212, v134
	v_cndmask_b32_e32 v214, 0, v135, vcc
	v_cmp_lt_f32_e32 vcc, s29, v193
	v_sub_f32_e32 v135, v192, v0
	v_exp_f32_e32 v135, v135
	v_cndmask_b32_e32 v215, 0, v136, vcc
	v_sub_f32_e32 v136, v196, v0
	v_exp_f32_e32 v136, v136
	v_cmp_lt_f32_e32 vcc, s29, v192
	v_add_f32_e32 v134, v215, v134
	v_add_f32_e32 v134, v214, v134
	v_cndmask_b32_e32 v216, 0, v135, vcc
	v_cmp_lt_f32_e32 vcc, s29, v196
	v_sub_f32_e32 v135, v194, v0
	v_exp_f32_e32 v135, v135
	v_cndmask_b32_e32 v196, 0, v136, vcc
	v_sub_f32_e32 v136, v198, v0
	v_exp_f32_e32 v136, v136
	v_cmp_lt_f32_e32 vcc, s29, v194
	v_add_f32_e32 v134, v196, v134
	v_add_f32_e32 v134, v216, v134
	v_cndmask_b32_e32 v194, 0, v135, vcc
	v_cmp_lt_f32_e32 vcc, s29, v198
	v_sub_f32_e32 v135, v195, v0
	v_exp_f32_e32 v135, v135
	v_cndmask_b32_e32 v198, 0, v136, vcc
	v_sub_f32_e32 v136, v199, v0
	v_exp_f32_e32 v136, v136
	v_cmp_lt_f32_e32 vcc, s29, v195
	v_add_f32_e32 v134, v198, v134
	v_add_f32_e32 v134, v194, v134
	v_cndmask_b32_e32 v195, 0, v135, vcc
	v_cmp_lt_f32_e32 vcc, s29, v199
	v_sub_f32_e32 v135, v197, v0
	v_exp_f32_e32 v135, v135
	v_cndmask_b32_e32 v199, 0, v136, vcc
	v_sub_f32_e32 v136, v201, v0
	v_exp_f32_e32 v136, v136
	v_cmp_lt_f32_e32 vcc, s29, v197
	v_add_f32_e32 v134, v199, v134
	v_add_f32_e32 v134, v195, v134
	v_cndmask_b32_e32 v197, 0, v135, vcc
	v_cmp_lt_f32_e32 vcc, s29, v201
	v_sub_f32_e32 v135, v200, v0
	v_exp_f32_e32 v135, v135
	v_cndmask_b32_e32 v201, 0, v136, vcc
	v_sub_f32_e32 v136, v203, v0
	v_exp_f32_e32 v136, v136
	v_cmp_lt_f32_e32 vcc, s29, v200
	v_add_f32_e32 v134, v201, v134
	v_add_f32_e32 v134, v197, v134
	v_cndmask_b32_e32 v200, 0, v135, vcc
	v_cmp_lt_f32_e32 vcc, s29, v203
	v_sub_f32_e32 v135, v202, v0
	v_exp_f32_e32 v135, v135
	v_cndmask_b32_e32 v203, 0, v136, vcc
	v_sub_f32_e32 v136, v205, v0
	v_exp_f32_e32 v136, v136
	v_cmp_lt_f32_e32 vcc, s29, v202
	v_add_f32_e32 v134, v203, v134
	v_add_f32_e32 v134, v200, v134
	v_cndmask_b32_e32 v202, 0, v135, vcc
	v_cmp_lt_f32_e32 vcc, s29, v205
	v_sub_f32_e32 v135, v139, v0
	v_exp_f32_e32 v186, v135
	v_cndmask_b32_e32 v205, 0, v136, vcc
	v_add_f32_e32 v134, v205, v134
	v_add_f32_e32 v217, v202, v134
	v_sub_f32_e32 v134, v204, v0
	v_exp_f32_e32 v134, v134
	v_cmp_lt_f32_e32 vcc, s29, v204
	v_cvt_pk_bf16_f32 v188, v210, v209
	v_cvt_pk_bf16_f32 v189, v189, v211
	v_cndmask_b32_e32 v204, 0, v134, vcc
	ds_read_b64_tr_b16 v[238:239], v218 offset:18432
	ds_read_b64_tr_b16 v[240:241], v218 offset:19200
	ds_read_b64_tr_b16 v[242:243], v218 offset:18496
	ds_read_b64_tr_b16 v[244:245], v218 offset:19264
	ds_read_b64_tr_b16 v[246:247], v218 offset:21504
	ds_read_b64_tr_b16 v[248:249], v218 offset:22272
	ds_read_b64_tr_b16 v[250:251], v218 offset:21568
	ds_read_b64_tr_b16 v[252:253], v218 offset:22336
	v_cmp_lt_f32_e32 vcc, s29, v139
	v_sub_f32_e32 v139, v132, v0
	v_exp_f32_e32 v139, v139
	v_cndmask_b32_e32 v219, 0, v186, vcc
	v_cvt_pk_bf16_f32 v186, v138, v206
	v_cmp_lt_f32_e32 vcc, s29, v132
	v_sub_f32_e32 v132, v129, v0
	s_nop 0
	s_waitcnt lgkmcnt(6)
	v_mfma_f32_32x32x16_bf16 v[2:17], v[238:241], v[186:189], v[2:17]
	ds_read_b64_tr_b16 v[238:239], v218 offset:24576
	ds_read_b64_tr_b16 v[240:241], v218 offset:25344
	v_add_f32_e32 v134, v219, v217
	v_add_f32_e32 v206, v204, v134
	v_sub_f32_e32 v134, v133, v0
	v_exp_f32_e32 v138, v134
	s_nop 0
	s_waitcnt lgkmcnt(6)
	v_mfma_f32_32x32x16_bf16 v[18:33], v[242:245], v[186:189], v[18:33]
	ds_read_b64_tr_b16 v[242:243], v218 offset:24640
	ds_read_b64_tr_b16 v[244:245], v218 offset:25408
	v_cvt_pk_bf16_f32 v186, v213, v212
	v_cvt_pk_bf16_f32 v187, v215, v214
	v_cvt_pk_bf16_f32 v188, v196, v216
	v_cvt_pk_bf16_f32 v189, v198, v194
	v_exp_f32_e32 v198, v132
	v_sub_f32_e32 v132, v131, v0
	s_nop 0
	s_waitcnt lgkmcnt(6)
	v_mfma_f32_32x32x16_bf16 v[2:17], v[246:249], v[186:189], v[2:17]
	ds_read_b64_tr_b16 v[246:247], v218 offset:27648
	ds_read_b64_tr_b16 v[248:249], v218 offset:28416
	v_cndmask_b32_e32 v194, 0, v139, vcc
	v_cmp_lt_f32_e32 vcc, s29, v133
	v_exp_f32_e32 v136, v132
	v_cndmask_b32_e32 v196, 0, v138, vcc
	v_cmp_lt_f32_e32 vcc, s29, v131
	v_sub_f32_e32 v131, v130, v0
	s_nop 0
	s_waitcnt lgkmcnt(6)
	v_mfma_f32_32x32x16_bf16 v[18:33], v[250:253], v[186:189], v[18:33]
	ds_read_b64_tr_b16 v[250:251], v218 offset:27712
	ds_read_b64_tr_b16 v[252:253], v218 offset:28480
	v_cndmask_b32_e32 v190, 0, v136, vcc
	v_cvt_pk_bf16_f32 v136, v199, v195
	v_cvt_pk_bf16_f32 v137, v201, v197
	v_cvt_pk_bf16_f32 v138, v203, v200
	v_cvt_pk_bf16_f32 v139, v205, v202
	v_exp_f32_e32 v131, v131
	v_cmp_lt_f32_e32 vcc, s29, v129
	s_nop 0
	s_waitcnt lgkmcnt(6)
	v_mfma_f32_32x32x16_bf16 v[2:17], v[238:241], v[136:139], v[2:17]
	v_sub_f32_e32 v132, v128, v0
	v_cndmask_b32_e32 v129, 0, v198, vcc
	v_exp_f32_e32 v134, v132
	v_cmp_lt_f32_e32 vcc, s29, v130
	v_cvt_pk_bf16_f32 v135, v196, v194
	s_nop 0
	v_cndmask_b32_e32 v191, 0, v131, vcc
	s_nop 0
	s_waitcnt lgkmcnt(4)
	v_mfma_f32_32x32x16_bf16 v[18:33], v[242:245], v[136:139], v[18:33]
	v_cmp_lt_f32_e32 vcc, s29, v128
	v_cvt_pk_bf16_f32 v136, v129, v190
	s_nop 0
	v_cndmask_b32_e32 v128, 0, v134, vcc
	v_cvt_pk_bf16_f32 v134, v219, v204
	v_cvt_pk_bf16_f32 v137, v128, v191
	s_nop 0
	s_nop 0
	s_waitcnt lgkmcnt(2)
	v_mfma_f32_32x32x16_bf16 v[2:17], v[246:249], v[134:137], v[2:17]
	v_add_f32_e32 v130, v196, v206
	v_add_f32_e32 v130, v194, v130
	v_add_f32_e32 v129, v129, v130
	v_add_f32_e32 v129, v190, v129
	v_add_f32_e32 v128, v128, v129
	v_add_f32_e32 v128, v191, v128
	v_add_f32_e32 v127, v128, v127
	s_nop 0
	s_waitcnt lgkmcnt(0)
	v_mfma_f32_32x32x16_bf16 v[18:33], v[250:253], v[134:137], v[18:33]

.LBB0_872:
	v_mov_b32_e32 v62, v165
	s_xor_b32 s64, s64, 1
	v_ashrrev_i32_e32 v63, 3, v62
	v_lshlrev_b32_e32 v62, 4, v62
	s_mul_i32 s18, s64, 0x2400
	v_mul_lo_u32 v64, v63, s93
	v_and_b32_e32 v62, 0x70, v62
	s_add_i32 s18, s18, 0
	s_mul_i32 s19, s64, 0xc00
	s_add_i32 s73, s73, 1
	v_add3_u32 v64, s18, v64, v62
	s_add_i32 s18, s18, s19
	v_mul_lo_u32 v63, v63, s87
	s_add_i32 s70, s70, 64
	v_add3_u32 v62, s18, v63, v62
	s_cmp_eq_u32 s71, s73
	v_subrev_u32_e32 v123, 64, v123
	s_waitcnt vmcnt(3)
	ds_write_b128 v64, v[82:85]
	s_waitcnt vmcnt(2)
	ds_write_b128 v62, v[86:89] offset:18432
	s_waitcnt lgkmcnt(0)
	s_barrier
	s_cbranch_scc1 .LBB0_875
	s_waitcnt vmcnt(1)
	v_mov_b64_e32 v[82:83], v[90:91]
	s_waitcnt vmcnt(0)
	v_mov_b64_e32 v[86:87], v[94:95]
	v_mov_b32_e32 v124, v127
	v_mov_b64_e32 v[84:85], v[92:93]
	v_mov_b64_e32 v[88:89], v[96:97]
	v_mov_b32_e32 v125, v0
	s_branch .LBB0_864

.LBB0_875:
	s_nop 7
	v_mov_b64_e32 v[34:35], v[2:3]
	v_mov_b64_e32 v[36:37], v[4:5]
	v_mov_b64_e32 v[38:39], v[6:7]
	v_mov_b64_e32 v[40:41], v[8:9]
	v_mov_b64_e32 v[42:43], v[10:11]
	v_mov_b64_e32 v[44:45], v[12:13]
	v_mov_b64_e32 v[46:47], v[14:15]
	v_mov_b64_e32 v[48:49], v[16:17]
	v_mov_b64_e32 v[50:51], v[18:19]
	v_mov_b64_e32 v[52:53], v[20:21]
	v_mov_b64_e32 v[54:55], v[22:23]
	v_mov_b64_e32 v[56:57], v[24:25]
	v_mov_b64_e32 v[58:59], v[26:27]
	v_mov_b64_e32 v[60:61], v[28:29]
	v_mov_b64_e32 v[62:63], v[30:31]
	v_mov_b64_e32 v[64:65], v[32:33]
	s_waitcnt vmcnt(1)
	v_mov_b64_e32 v[82:83], v[90:91]
	s_waitcnt vmcnt(0)
	v_mov_b64_e32 v[86:87], v[94:95]
	v_mov_b64_e32 v[84:85], v[92:93]
	v_mov_b64_e32 v[88:89], v[96:97]
